# v59 plus GEMM1 rotary-k epilogue: cos/sin table rows of all row groups loaded up front (counted vmcnt(14))
# speedup vs baseline: 1.0132x; 1.0132x over previous
.LBB0_551:
	s_andn2_b64 vcc, exec, s[4:5]
	s_cbranch_vccnz .LBB0_585
	v_add_u32_e32 v169, s57, v184
	s_lshl_b32 s6, s90, 8
	v_lshl_add_u32 v140, v185, 3, s59
	v_add_u32_e32 v144, s6, v169
	v_ashrrev_i32_e32 v128, 1, v140
	v_lshlrev_b32_e32 v131, 8, v185
	v_ashrrev_i32_e32 v145, 31, v144
	v_ashrrev_i32_e32 v129, 31, v128
	v_lshlrev_b32_e32 v130, 5, v140
	v_and_b32_e32 v131, 0x100, v131
	v_lshlrev_b64 v[132:133], 8, v[144:145]
	v_and_or_b32 v168, v130, s42, v131
	v_lshl_add_u64 v[130:131], s[12:13], 0, v[132:133]
	v_lshlrev_b64 v[142:143], 2, v[128:129]
	v_lshl_add_u64 v[132:133], s[14:15], 0, v[132:133]
	v_lshl_add_u64 v[128:129], v[130:131], 0, v[142:143]
	v_lshl_add_u64 v[132:133], v[132:133], 0, v[142:143]
	global_load_dwordx4 v[128:131], v[128:129], off
	v_lshlrev_b32_e32 v136, 7, v144
	global_load_dwordx4 v[132:135], v[132:133], off
	v_lshl_add_u32 v250, v144, 8, v142
	v_add_u32_e32 v251, 0x1000, v250
	global_load_dwordx4 v[192:195], v251, s[12:13]
	global_load_dwordx4 v[196:199], v251, s[14:15]
	v_add_u32_e32 v251, 0x2000, v250
	global_load_dwordx4 v[200:203], v251, s[12:13]
	global_load_dwordx4 v[204:207], v251, s[14:15]
	v_add_u32_e32 v251, 0x3000, v250
	global_load_dwordx4 v[210:213], v251, s[12:13]
	global_load_dwordx4 v[214:217], v251, s[14:15]
	v_add_u32_e32 v251, 0x8000, v250
	global_load_dwordx4 v[218:221], v251, s[12:13]
	global_load_dwordx4 v[222:225], v251, s[14:15]
	v_add_u32_e32 v251, 0x9000, v250
	global_load_dwordx4 v[226:229], v251, s[12:13]
	global_load_dwordx4 v[230:233], v251, s[14:15]
	v_add_u32_e32 v251, 0xa000, v250
	global_load_dwordx4 v[234:237], v251, s[12:13]
	global_load_dwordx4 v[238:241], v251, s[14:15]
	v_add_u32_e32 v251, 0xb000, v250
	global_load_dwordx4 v[242:245], v251, s[12:13]
	global_load_dwordx4 v[246:249], v251, s[14:15]
	v_and_b32_e32 v136, 0xfffff000, v136
	v_lshlrev_b32_e32 v137, 3, v184
	v_add_u32_e32 v136, v168, v136
	v_and_b32_e32 v145, 0xf8, v137
	v_or_b32_e32 v170, v136, v145
	s_lshl_b32 s20, s82, 9
	v_ashrrev_i32_e32 v141, 31, v140
	v_cmp_gt_i32_e32 vcc, s56, v144
	s_waitcnt vmcnt(14)
	v_pk_mul_f32 v[136:137], v[120:121], v[134:135] op_sel_hi:[1,0]
	s_nop 0
	v_pk_fma_f32 v[138:139], v[120:121], v[130:131], v[136:137] op_sel:[0,0,1] op_sel_hi:[1,0,0] neg_lo:[0,0,1] neg_hi:[0,0,1]
	v_pk_fma_f32 v[136:137], v[120:121], v[130:131], v[136:137] op_sel:[0,0,1] op_sel_hi:[1,0,0]
	v_mov_b32_e32 v146, v135
	v_mov_b32_e32 v136, v131
	v_pk_mul_f32 v[146:147], v[122:123], v[146:147] op_sel_hi:[1,0]
	v_mov_b32_e32 v139, v137
	v_pk_fma_f32 v[172:173], v[122:123], v[136:137], v[146:147] op_sel:[0,0,1] op_sel_hi:[1,0,0] neg_lo:[0,0,1] neg_hi:[0,0,1]
	v_pk_fma_f32 v[146:147], v[122:123], v[136:137], v[146:147] op_sel:[0,0,1] op_sel_hi:[1,0,0]
	v_pk_mul_f32 v[174:175], v[124:125], v[132:133] op_sel_hi:[1,0]
	v_mov_b32_e32 v173, v147
	v_pk_mul_f32 v[186:187], v[126:127], v[132:133] op_sel:[0,1]
	v_pk_mul_f32 v[146:147], v[172:173], s[30:31] op_sel_hi:[1,0]
	v_pk_mul_f32 v[138:139], v[138:139], s[30:31] op_sel_hi:[1,0]
	v_pk_fma_f32 v[176:177], v[124:125], v[128:129], v[174:175] op_sel:[0,0,1] op_sel_hi:[1,0,0] neg_lo:[0,0,1] neg_hi:[0,0,1]
	v_pk_fma_f32 v[174:175], v[124:125], v[128:129], v[174:175] op_sel:[0,0,1] op_sel_hi:[1,0,0]
	v_pk_fma_f32 v[188:189], v[126:127], v[128:129], v[186:187] op_sel:[0,1,1] op_sel_hi:[1,1,0] neg_lo:[0,0,1] neg_hi:[0,0,1]
	v_pk_fma_f32 v[186:187], v[126:127], v[128:129], v[186:187] op_sel:[0,1,1] op_sel_hi:[1,1,0]
	v_cvt_pk_bf16_f32 v138, v138, v139
	v_cvt_pk_bf16_f32 v139, v146, v147
	v_mov_b64_e32 v[146:147], s[0:1]
	v_mov_b32_e32 v189, v187
	v_mov_b32_e32 v177, v175
	v_mad_i64_i32 v[146:147], s[4:5], v144, s28, v[146:147]
	v_pk_mul_f32 v[186:187], v[188:189], s[30:31] op_sel_hi:[1,0]
	v_pk_mul_f32 v[174:175], v[176:177], s[30:31] op_sel_hi:[1,0]
	v_lshl_add_u64 v[146:147], v[146:147], 0, s[20:21]
	v_cvt_pk_bf16_f32 v136, v174, v175
	v_cvt_pk_bf16_f32 v137, v186, v187
	v_lshl_add_u64 v[146:147], v[140:141], 1, v[146:147]
	global_store_dwordx4 v[146:147], v[136:139], off
	s_and_saveexec_b64 s[4:5], vcc
	s_cbranch_execz .LBB0_554
	s_lshl_b32 s7, s82, 21
	s_add_i32 s7, s7, 0xff800000
	v_readlane_b32 s8, v252, 56
	v_add_u32_e32 v156, s7, v170
	v_readlane_b32 s9, v252, 57
	s_nop 1
	v_lshl_add_u64 v[172:173], v[156:157], 1, s[8:9]
	global_store_dwordx4 v[172:173], v[136:139], off

.LBB0_556:
	s_or_b64 exec, exec, s[4:5]
	v_add_u32_e32 v136, 16, v169
	v_add_u32_e32 v146, s6, v136
	v_ashrrev_i32_e32 v147, 31, v146
	v_lshlrev_b64 v[132:133], 8, v[146:147]
	v_lshl_add_u64 v[128:129], s[12:13], 0, v[132:133]
	v_lshl_add_u64 v[132:133], s[14:15], 0, v[132:133]
	v_lshl_add_u64 v[128:129], v[128:129], 0, v[142:143]
	v_lshl_add_u64 v[132:133], v[132:133], 0, v[142:143]
	v_lshlrev_b32_e32 v137, 7, v146
	v_and_b32_e32 v137, 0xfffff000, v137
	v_add_u32_e32 v137, v137, v168
	v_lshlrev_b32_e32 v136, 3, v136
	v_and_or_b32 v170, v136, s43, v137
	s_lshl_b32 s7, s82, 8
	v_cmp_gt_i32_e32 vcc, s56, v146
	s_lshl_b32 s20, s7, 1
	s_waitcnt vmcnt(14)
	v_mov_b32_e32 v128, v192
	v_mov_b32_e32 v129, v193
	v_mov_b32_e32 v130, v194
	v_mov_b32_e32 v131, v195
	v_mov_b32_e32 v132, v196
	v_mov_b32_e32 v133, v197
	v_mov_b32_e32 v134, v198
	v_mov_b32_e32 v135, v199
	v_pk_mul_f32 v[136:137], v[104:105], v[134:135] op_sel_hi:[1,0]
	s_nop 0
	v_pk_fma_f32 v[138:139], v[104:105], v[130:131], v[136:137] op_sel:[0,0,1] op_sel_hi:[1,0,0] neg_lo:[0,0,1] neg_hi:[0,0,1]
	v_pk_fma_f32 v[136:137], v[104:105], v[130:131], v[136:137] op_sel:[0,0,1] op_sel_hi:[1,0,0]
	v_mov_b32_e32 v156, v135
	v_mov_b32_e32 v136, v131
	v_pk_mul_f32 v[172:173], v[106:107], v[156:157] op_sel_hi:[1,0]
	v_mov_b32_e32 v139, v137
	v_pk_fma_f32 v[174:175], v[106:107], v[136:137], v[172:173] op_sel:[0,0,1] op_sel_hi:[1,0,0] neg_lo:[0,0,1] neg_hi:[0,0,1]
	v_pk_fma_f32 v[172:173], v[106:107], v[136:137], v[172:173] op_sel:[0,0,1] op_sel_hi:[1,0,0]
	v_pk_mul_f32 v[176:177], v[108:109], v[132:133] op_sel_hi:[1,0]
	v_mov_b32_e32 v175, v173
	v_pk_mul_f32 v[188:189], v[110:111], v[132:133] op_sel:[0,1]
	v_pk_mul_f32 v[172:173], v[174:175], s[30:31] op_sel_hi:[1,0]
	v_pk_mul_f32 v[138:139], v[138:139], s[30:31] op_sel_hi:[1,0]
	v_pk_fma_f32 v[186:187], v[108:109], v[128:129], v[176:177] op_sel:[0,0,1] op_sel_hi:[1,0,0] neg_lo:[0,0,1] neg_hi:[0,0,1]
	v_pk_fma_f32 v[176:177], v[108:109], v[128:129], v[176:177] op_sel:[0,0,1] op_sel_hi:[1,0,0]
	v_pk_fma_f32 v[190:191], v[110:111], v[128:129], v[188:189] op_sel:[0,1,1] op_sel_hi:[1,1,0] neg_lo:[0,0,1] neg_hi:[0,0,1]
	v_pk_fma_f32 v[188:189], v[110:111], v[128:129], v[188:189] op_sel:[0,1,1] op_sel_hi:[1,1,0]
	v_cvt_pk_bf16_f32 v138, v138, v139
	v_cvt_pk_bf16_f32 v139, v172, v173
	v_mov_b64_e32 v[172:173], s[0:1]
	v_mov_b32_e32 v191, v189
	v_mov_b32_e32 v187, v177
	v_mad_i64_i32 v[146:147], s[4:5], v146, s28, v[172:173]
	v_pk_mul_f32 v[188:189], v[190:191], s[30:31] op_sel_hi:[1,0]
	v_pk_mul_f32 v[176:177], v[186:187], s[30:31] op_sel_hi:[1,0]
	v_lshl_add_u64 v[146:147], v[146:147], 0, s[20:21]
	v_cvt_pk_bf16_f32 v136, v176, v177
	v_cvt_pk_bf16_f32 v137, v188, v189
	v_lshl_add_u64 v[146:147], v[140:141], 1, v[146:147]
	global_store_dwordx4 v[146:147], v[136:139], off
	s_and_saveexec_b64 s[4:5], vcc
	s_cbranch_execz .LBB0_558
	s_lshl_b32 s7, s82, 21
	s_add_i32 s7, s7, 0xff800000
	v_readlane_b32 s8, v252, 56
	v_add_u32_e32 v156, s7, v170
	v_readlane_b32 s9, v252, 57
	s_nop 1
	v_lshl_add_u64 v[172:173], v[156:157], 1, s[8:9]
	global_store_dwordx4 v[172:173], v[136:139], off

.LBB0_560:
	s_or_b64 exec, exec, s[4:5]
	v_add_u32_e32 v146, 32, v144
	v_ashrrev_i32_e32 v147, 31, v146
	v_lshlrev_b64 v[132:133], 8, v[146:147]
	v_lshl_add_u64 v[128:129], s[12:13], 0, v[132:133]
	v_lshl_add_u64 v[132:133], s[14:15], 0, v[132:133]
	v_lshl_add_u64 v[128:129], v[128:129], 0, v[142:143]
	v_lshl_add_u64 v[132:133], v[132:133], 0, v[142:143]
	v_lshlrev_b32_e32 v136, 7, v146
	v_and_b32_e32 v136, 0xfffff000, v136
	v_add_u32_e32 v136, v136, v168
	v_or_b32_e32 v170, v136, v145
	v_cmp_gt_i32_e32 vcc, s56, v146
	s_waitcnt vmcnt(14)
	v_mov_b32_e32 v128, v200
	v_mov_b32_e32 v129, v201
	v_mov_b32_e32 v130, v202
	v_mov_b32_e32 v131, v203
	v_mov_b32_e32 v132, v204
	v_mov_b32_e32 v133, v205
	v_mov_b32_e32 v134, v206
	v_mov_b32_e32 v135, v207
	v_pk_mul_f32 v[136:137], v[88:89], v[134:135] op_sel_hi:[1,0]
	s_nop 0
	v_pk_fma_f32 v[138:139], v[88:89], v[130:131], v[136:137] op_sel:[0,0,1] op_sel_hi:[1,0,0] neg_lo:[0,0,1] neg_hi:[0,0,1]
	v_pk_fma_f32 v[136:137], v[88:89], v[130:131], v[136:137] op_sel:[0,0,1] op_sel_hi:[1,0,0]
	v_mov_b32_e32 v156, v135
	v_mov_b32_e32 v136, v131
	v_pk_mul_f32 v[172:173], v[90:91], v[156:157] op_sel_hi:[1,0]
	v_mov_b32_e32 v139, v137
	v_pk_fma_f32 v[174:175], v[90:91], v[136:137], v[172:173] op_sel:[0,0,1] op_sel_hi:[1,0,0] neg_lo:[0,0,1] neg_hi:[0,0,1]
	v_pk_fma_f32 v[172:173], v[90:91], v[136:137], v[172:173] op_sel:[0,0,1] op_sel_hi:[1,0,0]
	v_pk_mul_f32 v[176:177], v[92:93], v[132:133] op_sel_hi:[1,0]
	v_mov_b32_e32 v175, v173
	v_pk_mul_f32 v[188:189], v[94:95], v[132:133] op_sel:[0,1]
	v_pk_mul_f32 v[172:173], v[174:175], s[30:31] op_sel_hi:[1,0]
	v_pk_mul_f32 v[138:139], v[138:139], s[30:31] op_sel_hi:[1,0]
	v_pk_fma_f32 v[186:187], v[92:93], v[128:129], v[176:177] op_sel:[0,0,1] op_sel_hi:[1,0,0] neg_lo:[0,0,1] neg_hi:[0,0,1]
	v_pk_fma_f32 v[176:177], v[92:93], v[128:129], v[176:177] op_sel:[0,0,1] op_sel_hi:[1,0,0]
	v_pk_fma_f32 v[190:191], v[94:95], v[128:129], v[188:189] op_sel:[0,1,1] op_sel_hi:[1,1,0] neg_lo:[0,0,1] neg_hi:[0,0,1]
	v_pk_fma_f32 v[188:189], v[94:95], v[128:129], v[188:189] op_sel:[0,1,1] op_sel_hi:[1,1,0]
	v_cvt_pk_bf16_f32 v138, v138, v139
	v_cvt_pk_bf16_f32 v139, v172, v173
	v_mov_b64_e32 v[172:173], s[0:1]
	v_mov_b32_e32 v191, v189
	v_mov_b32_e32 v187, v177
	v_mad_i64_i32 v[146:147], s[4:5], v146, s28, v[172:173]
	v_pk_mul_f32 v[188:189], v[190:191], s[30:31] op_sel_hi:[1,0]
	v_pk_mul_f32 v[176:177], v[186:187], s[30:31] op_sel_hi:[1,0]
	v_lshl_add_u64 v[146:147], v[146:147], 0, s[20:21]
	v_cvt_pk_bf16_f32 v136, v176, v177
	v_cvt_pk_bf16_f32 v137, v188, v189
	v_lshl_add_u64 v[146:147], v[140:141], 1, v[146:147]
	global_store_dwordx4 v[146:147], v[136:139], off
	s_and_saveexec_b64 s[4:5], vcc
	s_cbranch_execz .LBB0_562
	s_lshl_b32 s7, s82, 21
	s_add_i32 s7, s7, 0xff800000
	v_readlane_b32 s8, v252, 56
	v_add_u32_e32 v156, s7, v170
	v_readlane_b32 s9, v252, 57
	s_nop 1
	v_lshl_add_u64 v[172:173], v[156:157], 1, s[8:9]
	global_store_dwordx4 v[172:173], v[136:139], off

.LBB0_564:
	s_or_b64 exec, exec, s[4:5]
	v_add_u32_e32 v136, 48, v169
	v_add_u32_e32 v146, s6, v136
	v_ashrrev_i32_e32 v147, 31, v146
	v_lshlrev_b64 v[132:133], 8, v[146:147]
	v_lshl_add_u64 v[128:129], s[12:13], 0, v[132:133]
	v_lshl_add_u64 v[132:133], s[14:15], 0, v[132:133]
	v_lshl_add_u64 v[128:129], v[128:129], 0, v[142:143]
	v_lshl_add_u64 v[132:133], v[132:133], 0, v[142:143]
	v_lshlrev_b32_e32 v137, 7, v146
	v_and_b32_e32 v137, 0xfffff000, v137
	v_add_u32_e32 v137, v137, v168
	v_lshlrev_b32_e32 v136, 3, v136
	v_and_or_b32 v170, v136, s43, v137
	v_cmp_gt_i32_e32 vcc, s56, v146
	s_waitcnt vmcnt(14)
	v_mov_b32_e32 v128, v210
	v_mov_b32_e32 v129, v211
	v_mov_b32_e32 v130, v212
	v_mov_b32_e32 v131, v213
	v_mov_b32_e32 v132, v214
	v_mov_b32_e32 v133, v215
	v_mov_b32_e32 v134, v216
	v_mov_b32_e32 v135, v217
	v_pk_mul_f32 v[136:137], v[72:73], v[134:135] op_sel_hi:[1,0]
	s_nop 0
	v_pk_fma_f32 v[138:139], v[72:73], v[130:131], v[136:137] op_sel:[0,0,1] op_sel_hi:[1,0,0] neg_lo:[0,0,1] neg_hi:[0,0,1]
	v_pk_fma_f32 v[136:137], v[72:73], v[130:131], v[136:137] op_sel:[0,0,1] op_sel_hi:[1,0,0]
	v_mov_b32_e32 v156, v135
	v_mov_b32_e32 v136, v131
	v_pk_mul_f32 v[172:173], v[74:75], v[156:157] op_sel_hi:[1,0]
	v_mov_b32_e32 v139, v137
	v_pk_fma_f32 v[174:175], v[74:75], v[136:137], v[172:173] op_sel:[0,0,1] op_sel_hi:[1,0,0] neg_lo:[0,0,1] neg_hi:[0,0,1]
	v_pk_fma_f32 v[172:173], v[74:75], v[136:137], v[172:173] op_sel:[0,0,1] op_sel_hi:[1,0,0]
	v_pk_mul_f32 v[176:177], v[76:77], v[132:133] op_sel_hi:[1,0]
	v_mov_b32_e32 v175, v173
	v_pk_mul_f32 v[188:189], v[78:79], v[132:133] op_sel:[0,1]
	v_pk_mul_f32 v[172:173], v[174:175], s[30:31] op_sel_hi:[1,0]
	v_pk_mul_f32 v[138:139], v[138:139], s[30:31] op_sel_hi:[1,0]
	v_pk_fma_f32 v[186:187], v[76:77], v[128:129], v[176:177] op_sel:[0,0,1] op_sel_hi:[1,0,0] neg_lo:[0,0,1] neg_hi:[0,0,1]
	v_pk_fma_f32 v[176:177], v[76:77], v[128:129], v[176:177] op_sel:[0,0,1] op_sel_hi:[1,0,0]
	v_pk_fma_f32 v[190:191], v[78:79], v[128:129], v[188:189] op_sel:[0,1,1] op_sel_hi:[1,1,0] neg_lo:[0,0,1] neg_hi:[0,0,1]
	v_pk_fma_f32 v[188:189], v[78:79], v[128:129], v[188:189] op_sel:[0,1,1] op_sel_hi:[1,1,0]
	v_cvt_pk_bf16_f32 v138, v138, v139
	v_cvt_pk_bf16_f32 v139, v172, v173
	v_mov_b64_e32 v[172:173], s[0:1]
	v_mov_b32_e32 v191, v189
	v_mov_b32_e32 v187, v177
	v_mad_i64_i32 v[146:147], s[4:5], v146, s28, v[172:173]
	v_pk_mul_f32 v[188:189], v[190:191], s[30:31] op_sel_hi:[1,0]
	v_pk_mul_f32 v[176:177], v[186:187], s[30:31] op_sel_hi:[1,0]
	v_lshl_add_u64 v[146:147], v[146:147], 0, s[20:21]
	v_cvt_pk_bf16_f32 v136, v176, v177
	v_cvt_pk_bf16_f32 v137, v188, v189
	v_lshl_add_u64 v[146:147], v[140:141], 1, v[146:147]
	global_store_dwordx4 v[146:147], v[136:139], off
	s_and_saveexec_b64 s[4:5], vcc
	s_cbranch_execz .LBB0_566
	s_lshl_b32 s7, s82, 21
	s_add_i32 s7, s7, 0xff800000
	v_readlane_b32 s8, v252, 56
	v_add_u32_e32 v156, s7, v170
	v_readlane_b32 s9, v252, 57
	s_nop 1
	v_lshl_add_u64 v[172:173], v[156:157], 1, s[8:9]
	global_store_dwordx4 v[172:173], v[136:139], off

.LBB0_568:
	s_or_b64 exec, exec, s[4:5]
	v_add_u32_e32 v146, 0x80, v144
	v_ashrrev_i32_e32 v147, 31, v146
	v_lshlrev_b64 v[132:133], 8, v[146:147]
	v_lshl_add_u64 v[128:129], s[12:13], 0, v[132:133]
	v_lshl_add_u64 v[132:133], s[14:15], 0, v[132:133]
	v_lshl_add_u64 v[128:129], v[128:129], 0, v[142:143]
	v_lshl_add_u64 v[132:133], v[132:133], 0, v[142:143]
	v_lshlrev_b32_e32 v136, 7, v146
	v_and_b32_e32 v136, 0xfffff000, v136
	v_add_u32_e32 v136, v136, v168
	v_or_b32_e32 v170, v136, v145
	v_cmp_gt_i32_e32 vcc, s56, v146
	s_waitcnt vmcnt(14)
	v_mov_b32_e32 v128, v218
	v_mov_b32_e32 v129, v219
	v_mov_b32_e32 v130, v220
	v_mov_b32_e32 v131, v221
	v_mov_b32_e32 v132, v222
	v_mov_b32_e32 v133, v223
	v_mov_b32_e32 v134, v224
	v_mov_b32_e32 v135, v225
	v_pk_mul_f32 v[136:137], v[56:57], v[134:135] op_sel_hi:[1,0]
	s_nop 0
	v_pk_fma_f32 v[138:139], v[56:57], v[130:131], v[136:137] op_sel:[0,0,1] op_sel_hi:[1,0,0] neg_lo:[0,0,1] neg_hi:[0,0,1]
	v_pk_fma_f32 v[136:137], v[56:57], v[130:131], v[136:137] op_sel:[0,0,1] op_sel_hi:[1,0,0]
	v_mov_b32_e32 v156, v135
	v_mov_b32_e32 v136, v131
	v_pk_mul_f32 v[172:173], v[58:59], v[156:157] op_sel_hi:[1,0]
	v_mov_b32_e32 v139, v137
	v_pk_fma_f32 v[174:175], v[58:59], v[136:137], v[172:173] op_sel:[0,0,1] op_sel_hi:[1,0,0] neg_lo:[0,0,1] neg_hi:[0,0,1]
	v_pk_fma_f32 v[172:173], v[58:59], v[136:137], v[172:173] op_sel:[0,0,1] op_sel_hi:[1,0,0]
	v_pk_mul_f32 v[176:177], v[60:61], v[132:133] op_sel_hi:[1,0]
	v_mov_b32_e32 v175, v173
	v_pk_mul_f32 v[188:189], v[62:63], v[132:133] op_sel:[0,1]
	v_pk_mul_f32 v[172:173], v[174:175], s[30:31] op_sel_hi:[1,0]
	v_pk_mul_f32 v[138:139], v[138:139], s[30:31] op_sel_hi:[1,0]
	v_pk_fma_f32 v[186:187], v[60:61], v[128:129], v[176:177] op_sel:[0,0,1] op_sel_hi:[1,0,0] neg_lo:[0,0,1] neg_hi:[0,0,1]
	v_pk_fma_f32 v[176:177], v[60:61], v[128:129], v[176:177] op_sel:[0,0,1] op_sel_hi:[1,0,0]
	v_pk_fma_f32 v[190:191], v[62:63], v[128:129], v[188:189] op_sel:[0,1,1] op_sel_hi:[1,1,0] neg_lo:[0,0,1] neg_hi:[0,0,1]
	v_pk_fma_f32 v[188:189], v[62:63], v[128:129], v[188:189] op_sel:[0,1,1] op_sel_hi:[1,1,0]
	v_cvt_pk_bf16_f32 v138, v138, v139
	v_cvt_pk_bf16_f32 v139, v172, v173
	v_mov_b64_e32 v[172:173], s[0:1]
	v_mov_b32_e32 v191, v189
	v_mov_b32_e32 v187, v177
	v_mad_i64_i32 v[146:147], s[4:5], v146, s28, v[172:173]
	v_pk_mul_f32 v[188:189], v[190:191], s[30:31] op_sel_hi:[1,0]
	v_pk_mul_f32 v[176:177], v[186:187], s[30:31] op_sel_hi:[1,0]
	v_lshl_add_u64 v[146:147], v[146:147], 0, s[20:21]
	v_cvt_pk_bf16_f32 v136, v176, v177
	v_cvt_pk_bf16_f32 v137, v188, v189
	v_lshl_add_u64 v[146:147], v[140:141], 1, v[146:147]
	global_store_dwordx4 v[146:147], v[136:139], off
	s_and_saveexec_b64 s[4:5], vcc
	s_cbranch_execz .LBB0_570
	s_lshl_b32 s7, s82, 21
	s_add_i32 s7, s7, 0xff800000
	v_readlane_b32 s8, v252, 56
	v_add_u32_e32 v156, s7, v170
	v_readlane_b32 s9, v252, 57
	s_nop 1
	v_lshl_add_u64 v[172:173], v[156:157], 1, s[8:9]
	global_store_dwordx4 v[172:173], v[136:139], off

.LBB0_572:
	s_or_b64 exec, exec, s[4:5]
	v_add_u32_e32 v136, 0x90, v169
	v_add_u32_e32 v146, s6, v136
	v_ashrrev_i32_e32 v147, 31, v146
	v_lshlrev_b64 v[132:133], 8, v[146:147]
	v_lshl_add_u64 v[128:129], s[12:13], 0, v[132:133]
	v_lshl_add_u64 v[132:133], s[14:15], 0, v[132:133]
	v_lshl_add_u64 v[128:129], v[128:129], 0, v[142:143]
	v_lshl_add_u64 v[132:133], v[132:133], 0, v[142:143]
	v_lshlrev_b32_e32 v137, 7, v146
	v_and_b32_e32 v137, 0xfffff000, v137
	v_add_u32_e32 v137, v137, v168
	v_lshlrev_b32_e32 v136, 3, v136
	v_and_or_b32 v170, v136, s43, v137
	v_cmp_gt_i32_e32 vcc, s56, v146
	s_waitcnt vmcnt(14)
	v_mov_b32_e32 v128, v226
	v_mov_b32_e32 v129, v227
	v_mov_b32_e32 v130, v228
	v_mov_b32_e32 v131, v229
	v_mov_b32_e32 v132, v230
	v_mov_b32_e32 v133, v231
	v_mov_b32_e32 v134, v232
	v_mov_b32_e32 v135, v233
	v_pk_mul_f32 v[136:137], v[40:41], v[134:135] op_sel_hi:[1,0]
	s_nop 0
	v_pk_fma_f32 v[138:139], v[40:41], v[130:131], v[136:137] op_sel:[0,0,1] op_sel_hi:[1,0,0] neg_lo:[0,0,1] neg_hi:[0,0,1]
	v_pk_fma_f32 v[136:137], v[40:41], v[130:131], v[136:137] op_sel:[0,0,1] op_sel_hi:[1,0,0]
	v_mov_b32_e32 v156, v135
	v_mov_b32_e32 v136, v131
	v_pk_mul_f32 v[172:173], v[42:43], v[156:157] op_sel_hi:[1,0]
	v_mov_b32_e32 v139, v137
	v_pk_fma_f32 v[174:175], v[42:43], v[136:137], v[172:173] op_sel:[0,0,1] op_sel_hi:[1,0,0] neg_lo:[0,0,1] neg_hi:[0,0,1]
	v_pk_fma_f32 v[172:173], v[42:43], v[136:137], v[172:173] op_sel:[0,0,1] op_sel_hi:[1,0,0]
	v_pk_mul_f32 v[176:177], v[44:45], v[132:133] op_sel_hi:[1,0]
	v_mov_b32_e32 v175, v173
	v_pk_mul_f32 v[188:189], v[46:47], v[132:133] op_sel:[0,1]
	v_pk_mul_f32 v[172:173], v[174:175], s[30:31] op_sel_hi:[1,0]
	v_pk_mul_f32 v[138:139], v[138:139], s[30:31] op_sel_hi:[1,0]
	v_pk_fma_f32 v[186:187], v[44:45], v[128:129], v[176:177] op_sel:[0,0,1] op_sel_hi:[1,0,0] neg_lo:[0,0,1] neg_hi:[0,0,1]
	v_pk_fma_f32 v[176:177], v[44:45], v[128:129], v[176:177] op_sel:[0,0,1] op_sel_hi:[1,0,0]
	v_pk_fma_f32 v[190:191], v[46:47], v[128:129], v[188:189] op_sel:[0,1,1] op_sel_hi:[1,1,0] neg_lo:[0,0,1] neg_hi:[0,0,1]
	v_pk_fma_f32 v[188:189], v[46:47], v[128:129], v[188:189] op_sel:[0,1,1] op_sel_hi:[1,1,0]
	v_cvt_pk_bf16_f32 v138, v138, v139
	v_cvt_pk_bf16_f32 v139, v172, v173
	v_mov_b64_e32 v[172:173], s[0:1]
	v_mov_b32_e32 v191, v189
	v_mov_b32_e32 v187, v177
	v_mad_i64_i32 v[146:147], s[4:5], v146, s28, v[172:173]
	v_pk_mul_f32 v[188:189], v[190:191], s[30:31] op_sel_hi:[1,0]
	v_pk_mul_f32 v[176:177], v[186:187], s[30:31] op_sel_hi:[1,0]
	v_lshl_add_u64 v[146:147], v[146:147], 0, s[20:21]
	v_cvt_pk_bf16_f32 v136, v176, v177
	v_cvt_pk_bf16_f32 v137, v188, v189
	v_lshl_add_u64 v[146:147], v[140:141], 1, v[146:147]
	global_store_dwordx4 v[146:147], v[136:139], off
	s_and_saveexec_b64 s[4:5], vcc
	s_cbranch_execz .LBB0_574
	s_lshl_b32 s7, s82, 21
	s_add_i32 s7, s7, 0xff800000
	v_readlane_b32 s8, v252, 56
	v_add_u32_e32 v156, s7, v170
	v_readlane_b32 s9, v252, 57
	s_nop 1
	v_lshl_add_u64 v[172:173], v[156:157], 1, s[8:9]
	global_store_dwordx4 v[172:173], v[136:139], off

.LBB0_576:
	s_or_b64 exec, exec, s[4:5]
	v_add_u32_e32 v170, 0xa0, v144
	v_ashrrev_i32_e32 v171, 31, v170
	v_lshlrev_b64 v[132:133], 8, v[170:171]
	v_lshl_add_u64 v[128:129], s[12:13], 0, v[132:133]
	v_lshl_add_u64 v[132:133], s[14:15], 0, v[132:133]
	v_lshl_add_u64 v[128:129], v[128:129], 0, v[142:143]
	v_lshl_add_u64 v[132:133], v[132:133], 0, v[142:143]
	v_lshlrev_b32_e32 v136, 7, v170
	v_and_b32_e32 v136, 0xfffff000, v136
	v_add_u32_e32 v136, v136, v168
	v_or_b32_e32 v146, v136, v145
	v_cmp_gt_i32_e32 vcc, s56, v170
	s_waitcnt vmcnt(14)
	v_mov_b32_e32 v128, v234
	v_mov_b32_e32 v129, v235
	v_mov_b32_e32 v130, v236
	v_mov_b32_e32 v131, v237
	v_mov_b32_e32 v132, v238
	v_mov_b32_e32 v133, v239
	v_mov_b32_e32 v134, v240
	v_mov_b32_e32 v135, v241
	v_pk_mul_f32 v[136:137], v[24:25], v[134:135] op_sel_hi:[1,0]
	s_nop 0
	v_pk_fma_f32 v[138:139], v[24:25], v[130:131], v[136:137] op_sel:[0,0,1] op_sel_hi:[1,0,0] neg_lo:[0,0,1] neg_hi:[0,0,1]
	v_pk_fma_f32 v[136:137], v[24:25], v[130:131], v[136:137] op_sel:[0,0,1] op_sel_hi:[1,0,0]
	v_mov_b32_e32 v144, v135
	v_mov_b32_e32 v136, v131
	v_pk_mul_f32 v[144:145], v[26:27], v[144:145] op_sel_hi:[1,0]
	v_mov_b32_e32 v139, v137
	v_pk_fma_f32 v[172:173], v[26:27], v[136:137], v[144:145] op_sel:[0,0,1] op_sel_hi:[1,0,0] neg_lo:[0,0,1] neg_hi:[0,0,1]
	v_pk_fma_f32 v[144:145], v[26:27], v[136:137], v[144:145] op_sel:[0,0,1] op_sel_hi:[1,0,0]
	v_pk_mul_f32 v[174:175], v[28:29], v[132:133] op_sel_hi:[1,0]
	v_mov_b32_e32 v173, v145
	v_pk_mul_f32 v[186:187], v[30:31], v[132:133] op_sel:[0,1]
	v_pk_mul_f32 v[144:145], v[172:173], s[30:31] op_sel_hi:[1,0]
	v_pk_mul_f32 v[138:139], v[138:139], s[30:31] op_sel_hi:[1,0]
	v_pk_fma_f32 v[176:177], v[28:29], v[128:129], v[174:175] op_sel:[0,0,1] op_sel_hi:[1,0,0] neg_lo:[0,0,1] neg_hi:[0,0,1]
	v_pk_fma_f32 v[174:175], v[28:29], v[128:129], v[174:175] op_sel:[0,0,1] op_sel_hi:[1,0,0]
	v_pk_fma_f32 v[188:189], v[30:31], v[128:129], v[186:187] op_sel:[0,1,1] op_sel_hi:[1,1,0] neg_lo:[0,0,1] neg_hi:[0,0,1]
	v_pk_fma_f32 v[186:187], v[30:31], v[128:129], v[186:187] op_sel:[0,1,1] op_sel_hi:[1,1,0]
	v_cvt_pk_bf16_f32 v138, v138, v139
	v_cvt_pk_bf16_f32 v139, v144, v145
	v_mov_b64_e32 v[144:145], s[0:1]
	v_mov_b32_e32 v189, v187
	v_mov_b32_e32 v177, v175
	v_mad_i64_i32 v[144:145], s[4:5], v170, s28, v[144:145]
	v_pk_mul_f32 v[186:187], v[188:189], s[30:31] op_sel_hi:[1,0]
	v_pk_mul_f32 v[174:175], v[176:177], s[30:31] op_sel_hi:[1,0]
	v_lshl_add_u64 v[144:145], v[144:145], 0, s[20:21]
	v_cvt_pk_bf16_f32 v136, v174, v175
	v_cvt_pk_bf16_f32 v137, v186, v187
	v_lshl_add_u64 v[144:145], v[140:141], 1, v[144:145]
	global_store_dwordx4 v[144:145], v[136:139], off
	s_and_saveexec_b64 s[4:5], vcc
	s_cbranch_execz .LBB0_578
	s_lshl_b32 s7, s82, 21
	s_add_i32 s7, s7, 0xff800000
	v_readlane_b32 s8, v252, 56
	v_add_u32_e32 v156, s7, v146
	v_readlane_b32 s9, v252, 57
	s_nop 1
	v_lshl_add_u64 v[170:171], v[156:157], 1, s[8:9]
	global_store_dwordx4 v[170:171], v[136:139], off

.LBB0_580:
	s_or_b64 exec, exec, s[4:5]
	v_add_u32_e32 v136, 0xb0, v169
	v_add_u32_e32 v144, s6, v136
	v_ashrrev_i32_e32 v145, 31, v144
	v_lshlrev_b64 v[132:133], 8, v[144:145]
	v_lshl_add_u64 v[128:129], s[12:13], 0, v[132:133]
	v_lshl_add_u64 v[132:133], s[14:15], 0, v[132:133]
	v_lshl_add_u64 v[128:129], v[128:129], 0, v[142:143]
	v_lshl_add_u64 v[132:133], v[132:133], 0, v[142:143]
	v_lshlrev_b32_e32 v137, 7, v144
	v_and_b32_e32 v137, 0xfffff000, v137
	v_add_u32_e32 v137, v137, v168
	v_lshlrev_b32_e32 v136, 3, v136
	v_and_or_b32 v142, v136, s43, v137
	v_cmp_gt_i32_e32 vcc, s56, v144
	s_waitcnt vmcnt(14)
	v_mov_b32_e32 v128, v242
	v_mov_b32_e32 v129, v243
	v_mov_b32_e32 v130, v244
	v_mov_b32_e32 v131, v245
	v_mov_b32_e32 v132, v246
	v_mov_b32_e32 v133, v247
	v_mov_b32_e32 v134, v248
	v_mov_b32_e32 v135, v249
	v_pk_mul_f32 v[136:137], v[8:9], v[134:135] op_sel_hi:[1,0]
	s_nop 0
	v_pk_fma_f32 v[138:139], v[8:9], v[130:131], v[136:137] op_sel:[0,0,1] op_sel_hi:[1,0,0] neg_lo:[0,0,1] neg_hi:[0,0,1]
	v_pk_fma_f32 v[136:137], v[8:9], v[130:131], v[136:137] op_sel:[0,0,1] op_sel_hi:[1,0,0]
	v_mov_b32_e32 v146, v135
	v_mov_b32_e32 v136, v131
	v_pk_mul_f32 v[146:147], v[10:11], v[146:147] op_sel_hi:[1,0]
	v_mov_b32_e32 v139, v137
	v_pk_fma_f32 v[168:169], v[10:11], v[136:137], v[146:147] op_sel:[0,0,1] op_sel_hi:[1,0,0] neg_lo:[0,0,1] neg_hi:[0,0,1]
	v_pk_fma_f32 v[146:147], v[10:11], v[136:137], v[146:147] op_sel:[0,0,1] op_sel_hi:[1,0,0]
	v_pk_mul_f32 v[170:171], v[12:13], v[132:133] op_sel_hi:[1,0]
	v_mov_b32_e32 v169, v147
	v_pk_mul_f32 v[174:175], v[14:15], v[132:133] op_sel:[0,1]
	v_pk_mul_f32 v[146:147], v[168:169], s[30:31] op_sel_hi:[1,0]
	v_pk_mul_f32 v[138:139], v[138:139], s[30:31] op_sel_hi:[1,0]
	v_pk_fma_f32 v[172:173], v[12:13], v[128:129], v[170:171] op_sel:[0,0,1] op_sel_hi:[1,0,0] neg_lo:[0,0,1] neg_hi:[0,0,1]
	v_pk_fma_f32 v[170:171], v[12:13], v[128:129], v[170:171] op_sel:[0,0,1] op_sel_hi:[1,0,0]
	v_pk_fma_f32 v[176:177], v[14:15], v[128:129], v[174:175] op_sel:[0,1,1] op_sel_hi:[1,1,0] neg_lo:[0,0,1] neg_hi:[0,0,1]
	v_pk_fma_f32 v[174:175], v[14:15], v[128:129], v[174:175] op_sel:[0,1,1] op_sel_hi:[1,1,0]
	v_cvt_pk_bf16_f32 v138, v138, v139
	v_cvt_pk_bf16_f32 v139, v146, v147
	v_mov_b64_e32 v[146:147], s[0:1]
	v_mov_b32_e32 v177, v175
	v_mov_b32_e32 v173, v171
	v_mad_i64_i32 v[144:145], s[4:5], v144, s28, v[146:147]
	v_pk_mul_f32 v[174:175], v[176:177], s[30:31] op_sel_hi:[1,0]
	v_pk_mul_f32 v[170:171], v[172:173], s[30:31] op_sel_hi:[1,0]
	v_lshl_add_u64 v[144:145], v[144:145], 0, s[20:21]
	v_cvt_pk_bf16_f32 v136, v170, v171
	v_cvt_pk_bf16_f32 v137, v174, v175
	v_lshl_add_u64 v[140:141], v[140:141], 1, v[144:145]
	global_store_dwordx4 v[140:141], v[136:139], off
	s_and_saveexec_b64 s[4:5], vcc
	s_cbranch_execz .LBB0_582
	s_lshl_b32 s6, s82, 21
	s_add_i32 s6, s6, 0xff800000
	v_add_u32_e32 v156, s6, v142
	v_readlane_b32 s6, v252, 56
	v_readlane_b32 s7, v252, 57
	s_nop 1
	v_lshl_add_u64 v[144:145], v[156:157], 1, s[6:7]
	global_store_dwordx4 v[144:145], v[136:139], off
